# out-proj: per-row group rescale factors computed once per tile into LDS (static LDS +8448 B), sub-unit epilogues read them with ds_read instead of global loads
# speedup vs baseline: 1.0120x; 1.0107x over previous
; #define PG8_STAGE(bufoff, gbase, goff, voff) do { _Pragma("unroll") for (int _i = 0; _i < 2; ++_i) \
;     __builtin_amdgcn_global_load_lds((const unsigned*)((gbase) + (size_t)(goff) + (voff)[_i]), (LAS unsigned*)(lds + (bufoff) + ldsw + _i * 8192), 16, 0, 0); } while (0)
; #define PG8_WAIT_V(n) asm volatile("s_waitcnt vmcnt(" #n ")" ::: "memory")
; #define PG8_BAR __builtin_amdgcn_s_barrier()
; template <class Epi>
; DI void gemm_phase(LAS unsigned char* lds, const GemmD g, const Order& S, const Epi& E) {
;     ...
;   Unit cur, nxt; int ui = 0;
;   if (!S.next(0, cur)) return;
;   f32x4 acc[2][2][4][2];
; #pragma unroll
;   for (int a = 0; a < 2; ++a)
; #pragma unroll
;     for (int b = 0; b < 2; ++b)
; #pragma unroll
;       for (int m = 0; m < 4; ++m)
; #pragma unroll
;         for (int n = 0; n < 2; ++n) acc[a][b][m][n] = (f32x4){0.f, 0.f, 0.f, 0.f};
;   bf16x8 At[4][2], B0[2][2], B1[2][2];
;   unsigned cA = (unsigned)cur.pm * 2u * hstepA + (unsigned)cur.kg * ustep;
;   unsigned cB = (unsigned)cur.pn * 2u * hstepB + (unsigned)cur.kg * ustep;
;   PG8_STAGE(PG8_SB(0, 0), gB, cB, voffB); PG8_STAGE(PG8_SA(0, 0), gA, cA, voffA); PG8_STAGE(PG8_SB(0, 1), gB, cB + hstepB, voffB); PG8_STAGE(PG8_SA(0, 1), gA, cA + hstepA, voffA);
;   if (wr == 1) PG8_BAR;
;   PG8_WAIT_V(4); PG8_BAR;
;   PG8_STAGE(PG8_SB(1, 0), gB, cB + kstep, voffB); PG8_STAGE(PG8_SA(1, 0), gA, cA + kstep, voffA); PG8_STAGE(PG8_SB(1, 1), gB, cB + hstepB + kstep, voffB);
;   PG8_WAIT_V(6); PG8_BAR;
.LBB0_251:
	s_cmp_eq_u32 s64, 0
	s_waitcnt lgkmcnt(0)
	s_cselect_b32 s19, s7, s11
	s_mul_i32 s7, s64, 0xc000
	s_cselect_b32 s18, s6, s10
	s_mul_hi_u32 s6, s64, 0xc000
	s_add_u32 s8, s20, s7
	s_addc_u32 s9, s21, s6
	s_add_u32 s67, s8, 0x2000
	s_addc_u32 s68, s9, 0
	s_lshl_b32 s48, s64, 10
	s_lshl_b64 s[6:7], s[48:49], 2
	s_add_u32 s20, s4, s6
	s_addc_u32 s21, s5, s7
	v_and_b32_e32 v9, 15, v8
	s_add_u32 s69, s8, 0x4000
	v_and_b32_e32 v10, 48, v8
	v_lshlrev_b32_e32 v9, 6, v9
	v_lshlrev_b32_e32 v8, 2, v8
	s_addc_u32 s70, s9, 0
	v_or_b32_e32 v11, v9, v10
	s_lshl_b32 s4, s23, 13
	v_and_b32_e32 v8, 32, v8
	v_bitop3_b32 v9, v9, v8, v10 bitop3:0x36
	v_bitop3_b32 v8, v11, s4, v8 bitop3:0xde
	s_lshl_b32 s4, s22, 12
	s_and_b32 s4, s4, 0x3000
	s_add_i32 m0, s30, 0x18000
	v_lshl_add_u64 v[0:1], v[0:1], 0, s[50:51]
	v_or_b32_e32 v167, s4, v9
	s_waitcnt vmcnt(4)
	s_barrier
	global_load_lds_dwordx4 v[0:1], off
	v_lshl_add_u64 v[0:1], v[2:3], 0, s[50:51]
	s_add_i32 m0, s30, 0x1a000
	s_add_i32 s71, s30, 0x8000
	s_add_i32 s72, s30, 0xa000
	v_readlane_b32 s4, v255, 39
	global_load_lds_dwordx4 v[0:1], off
	v_lshl_add_u64 v[0:1], v[4:5], 0, s[50:51]
	s_mov_b32 m0, s71
	s_add_u32 s4, s27, s4
	global_load_lds_dwordx4 v[0:1], off
	v_lshl_add_u64 v[0:1], v[6:7], 0, s[50:51]
	s_mov_b32 m0, s72
	s_addc_u32 s5, s28, 0
	global_load_lds_dwordx4 v[0:1], off
	s_add_i32 m0, s30, 0x1c000
	v_lshl_add_u64 v[0:1], s[4:5], 0, v[32:33]
	global_load_lds_dwordx4 v[0:1], off
	v_lshl_add_u64 v[0:1], s[4:5], 0, v[146:147]
	s_add_i32 m0, s30, 0x1e000
	v_mov_b32_e32 v42, 0
	global_load_lds_dwordx4 v[0:1], off
	s_waitcnt vmcnt(6)
	s_mov_b32 s24, 0
	s_mov_b32 s98, 0
	s_mov_b32 s73, 1
	v_add_u32_e32 v216, 0, v8
	v_readlane_b32 s39, v255, 33
	v_readlane_b32 s38, v255, 34
	v_readlane_b32 s23, v255, 38
	v_readlane_b32 s22, v255, 36
	v_mov_b32_e32 v43, v42
	v_mov_b32_e32 v44, v42
	v_mov_b32_e32 v45, v42
	v_mov_b32_e32 v46, v42
	v_mov_b32_e32 v47, v42
	v_mov_b32_e32 v48, v42
	v_mov_b32_e32 v49, v42
	v_mov_b32_e32 v0, v42
	v_mov_b32_e32 v1, v42
	v_mov_b32_e32 v2, v42
	v_mov_b32_e32 v3, v42
	v_mov_b32_e32 v4, v42
	v_mov_b32_e32 v5, v42
	v_mov_b32_e32 v6, v42
	v_mov_b32_e32 v7, v42
	v_mov_b32_e32 v8, v42
	v_mov_b32_e32 v9, v42
	v_mov_b32_e32 v10, v42
	v_mov_b32_e32 v11, v42
	v_mov_b32_e32 v12, v42
	v_mov_b32_e32 v13, v42
	v_mov_b32_e32 v14, v42
	v_mov_b32_e32 v15, v42
	v_mov_b32_e32 v20, v42
	v_mov_b32_e32 v21, v42
	v_mov_b32_e32 v22, v42
	v_mov_b32_e32 v23, v42
	v_mov_b32_e32 v28, v42
	v_mov_b32_e32 v29, v42
	v_mov_b32_e32 v30, v42
	v_mov_b32_e32 v31, v42
	v_mov_b32_e32 v58, v42
	v_mov_b32_e32 v59, v42
	v_mov_b32_e32 v60, v42
	v_mov_b32_e32 v61, v42
	v_mov_b32_e32 v62, v42
	v_mov_b32_e32 v63, v42
	v_mov_b32_e32 v64, v42
	v_mov_b32_e32 v65, v42
	v_mov_b32_e32 v16, v42
	v_mov_b32_e32 v17, v42
	v_mov_b32_e32 v18, v42
	v_mov_b32_e32 v19, v42
	v_mov_b32_e32 v24, v42
	v_mov_b32_e32 v25, v42
	v_mov_b32_e32 v26, v42
	v_mov_b32_e32 v27, v42
	v_mov_b32_e32 v34, v42
	v_mov_b32_e32 v35, v42
	v_mov_b32_e32 v36, v42
	v_mov_b32_e32 v37, v42
	v_mov_b32_e32 v38, v42
	v_mov_b32_e32 v39, v42
	v_mov_b32_e32 v40, v42
	v_mov_b32_e32 v41, v42
	v_mov_b32_e32 v50, v42
	v_mov_b32_e32 v51, v42
	v_mov_b32_e32 v52, v42
	v_mov_b32_e32 v53, v42
	v_mov_b32_e32 v54, v42
	v_mov_b32_e32 v55, v42
	v_mov_b32_e32 v56, v42
	v_mov_b32_e32 v57, v42
	v_mov_b32_e32 v66, v42
	v_mov_b32_e32 v67, v42
	v_mov_b32_e32 v68, v42
	v_mov_b32_e32 v69, v42
	v_mov_b32_e32 v70, v42
	v_mov_b32_e32 v71, v42
	v_mov_b32_e32 v72, v42
	v_mov_b32_e32 v73, v42
	v_mov_b32_e32 v74, v42
	v_mov_b32_e32 v75, v42
	v_mov_b32_e32 v76, v42
	v_mov_b32_e32 v77, v42
	v_mov_b32_e32 v78, v42
	v_mov_b32_e32 v79, v42
	v_mov_b32_e32 v80, v42
	v_mov_b32_e32 v81, v42
	s_waitcnt vmcnt(0)
	v_mov_b32_e32 v82, v42
	v_mov_b32_e32 v83, v42
	v_mov_b32_e32 v84, v42
	v_mov_b32_e32 v85, v42
	v_mov_b32_e32 v86, v42
	v_mov_b32_e32 v87, v42
	v_mov_b32_e32 v88, v42
	v_mov_b32_e32 v89, v42
	v_mov_b32_e32 v98, v42
	v_mov_b32_e32 v99, v42
	v_mov_b32_e32 v100, v42
	v_mov_b32_e32 v101, v42
	v_mov_b32_e32 v102, v42
	v_mov_b32_e32 v103, v42
	v_mov_b32_e32 v104, v42
	v_mov_b32_e32 v105, v42
	v_mov_b32_e32 v90, v42
	v_mov_b32_e32 v91, v42
	v_mov_b32_e32 v92, v42
	v_mov_b32_e32 v93, v42
	v_mov_b32_e32 v94, v42
	v_mov_b32_e32 v95, v42
	v_mov_b32_e32 v96, v42
	v_mov_b32_e32 v97, v42
	v_mov_b32_e32 v106, v42
	v_mov_b32_e32 v107, v42
	v_mov_b32_e32 v108, v42
	v_mov_b32_e32 v109, v42
	v_mov_b32_e32 v110, v42
	v_mov_b32_e32 v111, v42
	v_mov_b32_e32 v112, v42
	v_mov_b32_e32 v113, v42
	v_mov_b32_e32 v114, v42
	v_mov_b32_e32 v115, v42
	v_mov_b32_e32 v116, v42
	v_mov_b32_e32 v117, v42
	v_mov_b32_e32 v118, v42
	v_mov_b32_e32 v119, v42
	v_mov_b32_e32 v120, v42
	v_mov_b32_e32 v121, v42
	v_mov_b32_e32 v122, v42
	v_mov_b32_e32 v123, v42
	v_mov_b32_e32 v124, v42
	v_mov_b32_e32 v125, v42
	v_mov_b32_e32 v126, v42
	v_mov_b32_e32 v127, v42
	v_mov_b32_e32 v128, v42
	v_mov_b32_e32 v129, v42
	s_barrier
	s_branch .LBB0_254

; #define PG8_STAGE(bufoff, gbase, goff, voff) do { _Pragma("unroll") for (int _i = 0; _i < 2; ++_i) \
;     __builtin_amdgcn_global_load_lds((const unsigned*)((gbase) + (size_t)(goff) + (voff)[_i]), (LAS unsigned*)(lds + (bufoff) + ldsw + _i * 8192), 16, 0, 0); } while (0)
; #define PG8_LDA(dst, b, h) do { _Pragma("unroll") for (int m = 0; m < 4; ++m) _Pragma("unroll") for (int k = 0; k < 2; ++k) dst[m][k] = *(const LAS bf16x8*)(lds + PG8_SA(b, h) + aoff + m * 2048 + k * 1024); } while (0)
; #define PG8_LDB(dst, b, h) do { _Pragma("unroll") for (int n = 0; n < 2; ++n) _Pragma("unroll") for (int k = 0; k < 2; ++k) dst[n][k] = *(const LAS bf16x8*)(lds + PG8_SB(b, h) + boff + n * 2048 + k * 1024); } while (0)
; #define PG8_WAIT_V(n) asm volatile("s_waitcnt vmcnt(" #n ")" ::: "memory")
; #define PG8_WAIT_L(n) asm volatile("s_waitcnt lgkmcnt(" #n ")" ::: "memory")
; #define PG8_BAR __builtin_amdgcn_s_barrier()
; #define PG8_SCHED __builtin_amdgcn_sched_barrier(0)
; template <class Epi>
; DI void gemm_phase(LAS unsigned char* lds, const GemmD g, const Order& S, const Epi& E) {
;     ...
;       PG8_LDB(B0, 0, 0); PG8_SCHED; PG8_LDA(At, 0, 0); PG8_STAGE(PG8_SA(1, 1), gA, a1 + hstepA, voffA);
;       PG8_WAIT_L(8); PG8_BAR; PG8_WAIT_L(0); PG8_MMA(0, 0, At, B0); PG8_BAR; PG8_SCHED;
;       PG8_LDB(B1, 0, 1); PG8_STAGE(PG8_SB(0, 0), gB, b2, voffB);
;       PG8_BAR; PG8_WAIT_L(0); PG8_MMA(0, 1, At, B1); PG8_BAR;
;       PG8_LDA(At, 0, 1); PG8_STAGE(PG8_SA(0, 0), gA, a2, voffA);
;       PG8_BAR; PG8_WAIT_L(0); PG8_MMA(1, 0, At, B0); PG8_BAR; PG8_SCHED;
;       PG8_STAGE(PG8_SB(0, 1), gB, b2 + hstepB, voffB);
;       PG8_WAIT_V(6); PG8_BAR; PG8_MMA(1, 1, At, B1); PG8_BAR;
;   DI bool operator()(f32x4 (&acc)[2][2][4][2], const Unit& u, int, int, int, int) const {
;     ...
;           const int r = row0 + ai * HALF + m * 16;
;           const f32x4 q0 = *(const f32x4*)(ss + ((size_t)r * 4 + u.kg) * 4);
;           const float s0 = (q0[0] + q0[1] + q0[2] + q0[3]) * (1.f / 256.f) + 1e-6f;
;           float f;
;           if (u.kg < 3) { const f32x4 q1 = *(const f32x4*)(ss + ((size_t)r * 4 + u.kg + 1) * 4);
;             const float s1 = (q1[0] + q1[1] + q1[2] + q1[3]) * (1.f / 256.f) + 1e-6f; f = __builtin_amdgcn_sqrtf(s1) * __builtin_amdgcn_rsqf(s0); }
;           else f = __builtin_amdgcn_rsqf(s0);
.LBB0_260:
	s_cmp_eq_u32 s24, 0
	s_cbranch_scc0 .Lop_nof
	s_xor_b32 s98, s98, 1
	v_mov_b32_e32 v158, v202
	s_nop 0
	v_cmp_gt_u32_e32 vcc, 0x100, v158
	s_and_saveexec_b64 s[8:9], vcc
	s_cbranch_execz .Lop_nof2
	v_lshl_add_u32 v162, s38, 8, v158
	v_mov_b32_e32 v163, 0
	v_lshlrev_b64 v[162:163], 6, v[162:163]
	v_lshl_add_u64 v[162:163], s[16:17], 0, v[162:163]
	global_load_dwordx4 v[168:171], v[162:163], off
	global_load_dwordx4 v[172:175], v[162:163], off offset:16
	global_load_dwordx4 v[176:179], v[162:163], off offset:32
	global_load_dwordx4 v[180:183], v[162:163], off offset:48
	s_lshl_b32 s6, s98, 12
	s_add_i32 s6, s6, 0x20080
	v_lshl_add_u32 v164, v158, 4, s6
	s_waitcnt vmcnt(0)
	v_add_f32_e32 v184, v168, v169
	v_add_f32_e32 v184, v170, v184
	v_add_f32_e32 v184, v171, v184
	v_fmamk_f32 v184, v184, 0x3b800000, v203
	v_add_f32_e32 v185, v172, v173
	v_add_f32_e32 v185, v174, v185
	v_add_f32_e32 v185, v175, v185
	v_fmamk_f32 v185, v185, 0x3b800000, v203
	v_add_f32_e32 v186, v176, v177
	v_add_f32_e32 v186, v178, v186
	v_add_f32_e32 v186, v179, v186
	v_fmamk_f32 v186, v186, 0x3b800000, v203
	v_add_f32_e32 v187, v180, v181
	v_add_f32_e32 v187, v182, v187
	v_add_f32_e32 v187, v183, v187
	v_fmamk_f32 v187, v187, 0x3b800000, v203
	v_rsq_f32_e32 v188, v184
	v_rsq_f32_e32 v189, v185
	v_rsq_f32_e32 v190, v186
	v_rsq_f32_e32 v191, v187
	v_sqrt_f32_e32 v192, v185
	v_sqrt_f32_e32 v193, v186
	v_sqrt_f32_e32 v194, v187
	s_nop 0
	v_mul_f32_e32 v196, v188, v192
	v_mul_f32_e32 v197, v189, v193
	v_mul_f32_e32 v198, v190, v194
	v_mov_b32_e32 v199, v191
	ds_write_b128 v164, v[196:199]
	s_waitcnt lgkmcnt(0)
.Lop_nof2:
	s_or_b64 exec, exec, s[8:9]
.Lop_nof:
	s_and_b32 s77, s73, 3
	s_lshl_b32 s6, s75, 19
	s_lshl_b32 s8, s77, 9
	s_or_b32 s76, s6, s8
	s_and_b64 s[6:7], s[4:5], exec
	s_cselect_b32 s7, s76, s22
	s_lshl_b32 s6, s74, 19
	s_or_b32 s78, s6, s8
	s_and_b64 s[80:81], s[4:5], exec
	s_cselect_b32 s6, s78, s23
	s_add_i32 s8, 0, 0x10000
	v_add_u32_e32 v200, s8, v167
	s_waitcnt lgkmcnt(0)
	ds_read_b128 v[130:133], v200
	ds_read_b128 v[134:137], v200 offset:1024
	ds_read_b128 v[138:141], v200 offset:2048
	ds_read_b128 v[142:145], v200 offset:3072
	s_add_i32 s9, s22, 0x40080
	s_add_u32 s80, s14, s9
	s_addc_u32 s81, s15, 0
	s_add_i32 s90, s30, 0xc000
	v_lshl_add_u64 v[152:153], s[80:81], 0, v[32:33]
	s_mov_b32 m0, s90
	s_add_i32 s25, s30, 0xe000
	ds_read_b128 v[148:151], v216
	ds_read_b128 v[168:171], v216 offset:1024
	ds_read_b128 v[172:175], v216 offset:2048
	ds_read_b128 v[176:179], v216 offset:3072
	ds_read_b128 v[180:183], v216 offset:4096
	ds_read_b128 v[184:187], v216 offset:5120
	ds_read_b128 v[188:191], v216 offset:6144
	ds_read_b128 v[192:195], v216 offset:7168
	global_load_lds_dwordx4 v[152:153], off
	v_lshl_add_u64 v[152:153], s[80:81], 0, v[146:147]
	s_mov_b32 m0, s25
	s_nop 0
	global_load_lds_dwordx4 v[152:153], off
	s_waitcnt lgkmcnt(8)
	s_barrier
	s_waitcnt lgkmcnt(0)
	s_setprio 1
	s_waitcnt lgkmcnt(0)
	v_mfma_f32_16x16x32_bf16 v[118:121], v[130:133], v[172:175], v[118:121]
	v_mfma_f32_16x16x32_bf16 v[114:117], v[138:141], v[172:175], v[114:117]
	v_mfma_f32_16x16x32_bf16 v[110:113], v[130:133], v[180:183], v[110:113]
	v_mfma_f32_16x16x32_bf16 v[106:109], v[138:141], v[180:183], v[106:109]
	v_mfma_f32_16x16x32_bf16 v[94:97], v[130:133], v[188:191], v[94:97]
	v_mfma_f32_16x16x32_bf16 v[90:93], v[138:141], v[188:191], v[90:93]
	v_mfma_f32_16x16x32_bf16 v[126:129], v[130:133], v[148:151], v[126:129]
	v_mfma_f32_16x16x32_bf16 v[122:125], v[138:141], v[148:151], v[122:125]
	v_mfma_f32_16x16x32_bf16 v[118:121], v[134:137], v[176:179], v[118:121]
	v_mfma_f32_16x16x32_bf16 v[114:117], v[142:145], v[176:179], v[114:117]
	v_mfma_f32_16x16x32_bf16 v[110:113], v[134:137], v[184:187], v[110:113]
	v_mfma_f32_16x16x32_bf16 v[106:109], v[142:145], v[184:187], v[106:109]
	v_mfma_f32_16x16x32_bf16 v[94:97], v[134:137], v[192:195], v[94:97]
	v_mfma_f32_16x16x32_bf16 v[90:93], v[142:145], v[192:195], v[90:93]
	v_mfma_f32_16x16x32_bf16 v[126:129], v[134:137], v[168:171], v[126:129]
	v_mfma_f32_16x16x32_bf16 v[122:125], v[142:145], v[168:171], v[122:125]
	s_setprio 0
	s_barrier
	s_add_i32 s92, 0, 0x14000
	s_add_u32 vcc_lo, s27, s23
	s_addc_u32 vcc_hi, s28, 0
	v_lshl_add_u64 v[152:153], vcc, 0, v[32:33]
	s_add_i32 s80, s8, s29
	v_add_u32_e32 v201, s92, v167
	v_lshl_add_u64 v[158:159], v[152:153], 0, s[52:53]
	s_mov_b32 m0, s80
	ds_read_b128 v[196:199], v201
	ds_read_b128 v[218:221], v201 offset:1024
	ds_read_b128 v[222:225], v201 offset:2048
	ds_read_b128 v[226:229], v201 offset:3072
	global_load_lds_dwordx4 v[158:159], off
	v_lshl_add_u64 v[158:159], vcc, 0, v[146:147]
	s_add_i32 s48, s80, 0x2000
	v_lshl_add_u64 v[160:161], v[158:159], 0, s[52:53]
	s_mov_b32 m0, s48
	s_nop 0
	global_load_lds_dwordx4 v[160:161], off
	s_barrier
	s_waitcnt lgkmcnt(0)
	s_setprio 1
	s_waitcnt lgkmcnt(0)
	v_mfma_f32_16x16x32_bf16 v[102:105], v[196:199], v[148:151], v[102:105]
	v_mfma_f32_16x16x32_bf16 v[98:101], v[222:225], v[148:151], v[98:101]
	v_mfma_f32_16x16x32_bf16 v[86:89], v[196:199], v[172:175], v[86:89]
	v_mfma_f32_16x16x32_bf16 v[82:85], v[222:225], v[172:175], v[82:85]
	v_mfma_f32_16x16x32_bf16 v[78:81], v[196:199], v[180:183], v[78:81]
	v_mfma_f32_16x16x32_bf16 v[74:77], v[222:225], v[180:183], v[74:77]
	v_mfma_f32_16x16x32_bf16 v[70:73], v[196:199], v[188:191], v[70:73]
	v_mfma_f32_16x16x32_bf16 v[66:69], v[222:225], v[188:191], v[66:69]
	v_mfma_f32_16x16x32_bf16 v[102:105], v[218:221], v[168:171], v[102:105]
	v_mfma_f32_16x16x32_bf16 v[98:101], v[226:229], v[168:171], v[98:101]
	v_mfma_f32_16x16x32_bf16 v[86:89], v[218:221], v[176:179], v[86:89]
	v_mfma_f32_16x16x32_bf16 v[82:85], v[226:229], v[176:179], v[82:85]
	v_mfma_f32_16x16x32_bf16 v[78:81], v[218:221], v[184:187], v[78:81]
	v_mfma_f32_16x16x32_bf16 v[74:77], v[226:229], v[184:187], v[74:77]
	v_mfma_f32_16x16x32_bf16 v[70:73], v[218:221], v[192:195], v[70:73]
	v_mfma_f32_16x16x32_bf16 v[66:69], v[226:229], v[192:195], v[66:69]
	s_setprio 0
	s_add_u32 vcc_lo, s14, s22
	s_addc_u32 vcc_hi, s15, 0
	v_lshl_add_u64 v[160:161], vcc, 0, v[32:33]
	s_mov_b32 m0, s30
	v_lshl_add_u64 v[162:163], v[160:161], 0, s[52:53]
	s_barrier
; #define PG8_STAGE(bufoff, gbase, goff, voff) do { _Pragma("unroll") for (int _i = 0; _i < 2; ++_i) \
;     __builtin_amdgcn_global_load_lds((const unsigned*)((gbase) + (size_t)(goff) + (voff)[_i]), (LAS unsigned*)(lds + (bufoff) + ldsw + _i * 8192), 16, 0, 0); } while (0)
; #define PG8_LDA(dst, b, h) do { _Pragma("unroll") for (int m = 0; m < 4; ++m) _Pragma("unroll") for (int k = 0; k < 2; ++k) dst[m][k] = *(const LAS bf16x8*)(lds + PG8_SA(b, h) + aoff + m * 2048 + k * 1024); } while (0)
; #define PG8_LDB(dst, b, h) do { _Pragma("unroll") for (int n = 0; n < 2; ++n) _Pragma("unroll") for (int k = 0; k < 2; ++k) dst[n][k] = *(const LAS bf16x8*)(lds + PG8_SB(b, h) + boff + n * 2048 + k * 1024); } while (0)
; #define PG8_MMA(ai, bj, At, Bt) do { __builtin_amdgcn_s_setprio(1); _Pragma("unroll") for (int m = 0; m < 4; ++m) _Pragma("unroll") for (int n = 0; n < 2; ++n) _Pragma("unroll") for (int k = 0; k < 2; ++k) \
;     acc[ai][bj][m][n] = __builtin_amdgcn_mfma_f32_16x16x32_bf16(Bt[n][k], At[m][k], acc[ai][bj][m][n], 0, 0, 0); __builtin_amdgcn_s_setprio(0); } while (0)
; #define PG8_WAIT_V(n) asm volatile("s_waitcnt vmcnt(" #n ")" ::: "memory")
; #define PG8_WAIT_L(n) asm volatile("s_waitcnt lgkmcnt(" #n ")" ::: "memory")
; #define PG8_BAR __builtin_amdgcn_s_barrier()
; #define PG8_SCHED __builtin_amdgcn_sched_barrier(0)
; template <class Epi>
; DI void gemm_phase(LAS unsigned char* lds, const GemmD g, const Order& S, const Epi& E) {
;     ...
;       PG8_WAIT_V(6); PG8_BAR; PG8_MMA(1, 1, At, B1); PG8_BAR;
;       PG8_LDB(B0, 1, 0); PG8_SCHED; PG8_LDA(At, 1, 0); PG8_STAGE(PG8_SA(0, 1), gA, a2 + hstepA, voffA);
;       PG8_WAIT_L(8); PG8_BAR; PG8_WAIT_L(0); PG8_MMA(0, 0, At, B0); PG8_BAR; PG8_SCHED;
;       PG8_LDB(B1, 1, 1); PG8_STAGE(PG8_SB(1, 0), gB, b3, voffB);
;       PG8_BAR; PG8_WAIT_L(0); PG8_MMA(0, 1, At, B1); PG8_BAR;
;       PG8_LDA(At, 1, 1); PG8_STAGE(PG8_SA(1, 0), gA, a3, voffA);
	ds_read_b128 v[148:151], v216 offset:16384
	ds_read_b128 v[168:171], v216 offset:17408
	ds_read_b128 v[172:175], v216 offset:18432
	ds_read_b128 v[176:179], v216 offset:19456
	ds_read_b128 v[180:183], v216 offset:20480
	ds_read_b128 v[184:187], v216 offset:21504
	ds_read_b128 v[188:191], v216 offset:22528
	ds_read_b128 v[192:195], v216 offset:23552
	global_load_lds_dwordx4 v[162:163], off
	v_lshl_add_u64 v[162:163], vcc, 0, v[146:147]
	v_lshl_add_u64 v[164:165], v[162:163], 0, s[52:53]
	s_mov_b32 m0, s31
	s_nop 0
	global_load_lds_dwordx4 v[164:165], off
	s_barrier
	s_waitcnt lgkmcnt(0)
	s_setprio 1
	s_waitcnt lgkmcnt(0)
	v_mfma_f32_16x16x32_bf16 v[54:57], v[130:133], v[148:151], v[54:57]
	v_mfma_f32_16x16x32_bf16 v[50:53], v[138:141], v[148:151], v[50:53]
	v_mfma_f32_16x16x32_bf16 v[38:41], v[130:133], v[172:175], v[38:41]
	v_mfma_f32_16x16x32_bf16 v[34:37], v[138:141], v[172:175], v[34:37]
	v_mfma_f32_16x16x32_bf16 v[16:19], v[138:141], v[180:183], v[16:19]
	v_mfma_f32_16x16x32_bf16 v[62:65], v[130:133], v[188:191], v[62:65]
	v_mfma_f32_16x16x32_bf16 v[58:61], v[138:141], v[188:191], v[58:61]
	v_mfma_f32_16x16x32_bf16 v[54:57], v[134:137], v[168:171], v[54:57]
	v_mfma_f32_16x16x32_bf16 v[50:53], v[142:145], v[168:171], v[50:53]
	v_mfma_f32_16x16x32_bf16 v[38:41], v[134:137], v[176:179], v[38:41]
	v_mfma_f32_16x16x32_bf16 v[34:37], v[142:145], v[176:179], v[34:37]
	v_mfma_f32_16x16x32_bf16 v[24:27], v[130:133], v[180:183], v[24:27]
	v_mfma_f32_16x16x32_bf16 v[16:19], v[142:145], v[184:187], v[16:19]
	v_mfma_f32_16x16x32_bf16 v[62:65], v[134:137], v[192:195], v[62:65]
	v_mfma_f32_16x16x32_bf16 v[58:61], v[142:145], v[192:195], v[58:61]
	v_mfma_f32_16x16x32_bf16 v[24:27], v[134:137], v[184:187], v[24:27]
	s_setprio 0
	s_barrier
	s_add_i32 s8, s23, 0x40100
	s_add_u32 vcc_lo, s27, s8
	s_addc_u32 vcc_hi, s28, 0
	s_add_i32 s92, s92, s29
	v_lshl_add_u64 v[130:131], vcc, 0, v[32:33]
	s_mov_b32 m0, s92
	s_add_i32 s79, s92, 0x2000
	global_load_lds_dwordx4 v[130:131], off
	v_lshl_add_u64 v[130:131], vcc, 0, v[146:147]
	s_mov_b32 m0, s79
	s_nop 0
	global_load_lds_dwordx4 v[130:131], off
	s_waitcnt vmcnt(6)
	s_barrier
	s_setprio 1
	v_mfma_f32_16x16x32_bf16 v[28:31], v[196:199], v[148:151], v[28:31]
	v_mfma_f32_16x16x32_bf16 v[20:23], v[222:225], v[148:151], v[20:23]
	v_mfma_f32_16x16x32_bf16 v[12:15], v[196:199], v[172:175], v[12:15]
	v_mfma_f32_16x16x32_bf16 v[8:11], v[222:225], v[172:175], v[8:11]
	v_mfma_f32_16x16x32_bf16 v[4:7], v[196:199], v[180:183], v[4:7]
	v_mfma_f32_16x16x32_bf16 v[0:3], v[222:225], v[180:183], v[0:3]
	v_mfma_f32_16x16x32_bf16 v[46:49], v[196:199], v[188:191], v[46:49]
	v_mfma_f32_16x16x32_bf16 v[42:45], v[222:225], v[188:191], v[42:45]
	v_mfma_f32_16x16x32_bf16 v[28:31], v[218:221], v[168:171], v[28:31]
	v_mfma_f32_16x16x32_bf16 v[20:23], v[226:229], v[168:171], v[20:23]
	v_mfma_f32_16x16x32_bf16 v[12:15], v[218:221], v[176:179], v[12:15]
	v_mfma_f32_16x16x32_bf16 v[8:11], v[226:229], v[176:179], v[8:11]
	v_mfma_f32_16x16x32_bf16 v[4:7], v[218:221], v[184:187], v[4:7]
	v_mfma_f32_16x16x32_bf16 v[0:3], v[226:229], v[184:187], v[0:3]
	v_mfma_f32_16x16x32_bf16 v[46:49], v[218:221], v[192:195], v[46:49]
	v_mfma_f32_16x16x32_bf16 v[42:45], v[226:229], v[192:195], v[42:45]
	s_setprio 0
	s_add_i32 s95, 0, 0x18000
	v_add_u32_e32 v217, s95, v167
	s_barrier
	ds_read_b128 v[130:133], v217
	ds_read_b128 v[134:137], v217 offset:1024
	ds_read_b128 v[138:141], v217 offset:2048
	ds_read_b128 v[142:145], v217 offset:3072
	s_add_i32 s8, s22, 0x40100
	s_add_u32 vcc_lo, s14, s8
	s_addc_u32 vcc_hi, s15, 0
	s_mov_b32 m0, s65
	v_lshl_add_u64 v[164:165], vcc, 0, v[32:33]
	ds_read_b128 v[148:151], v216 offset:32768
	ds_read_b128 v[168:171], v216 offset:33792
	ds_read_b128 v[172:175], v216 offset:34816
	ds_read_b128 v[176:179], v216 offset:35840
	ds_read_b128 v[180:183], v216 offset:36864
	ds_read_b128 v[184:187], v216 offset:37888
	ds_read_b128 v[188:191], v216 offset:38912
	ds_read_b128 v[192:195], v216 offset:39936
	global_load_lds_dwordx4 v[164:165], off
	v_lshl_add_u64 v[164:165], vcc, 0, v[146:147]
	s_mov_b32 m0, s66
	s_nop 0
	global_load_lds_dwordx4 v[164:165], off
	s_waitcnt lgkmcnt(8)
	s_barrier
	s_waitcnt lgkmcnt(0)
	s_setprio 1
	s_waitcnt lgkmcnt(0)
	v_mfma_f32_16x16x32_bf16 v[118:121], v[130:133], v[172:175], v[118:121]
	v_mfma_f32_16x16x32_bf16 v[114:117], v[138:141], v[172:175], v[114:117]
	v_mfma_f32_16x16x32_bf16 v[110:113], v[130:133], v[180:183], v[110:113]
	v_mfma_f32_16x16x32_bf16 v[106:109], v[138:141], v[180:183], v[106:109]
	v_mfma_f32_16x16x32_bf16 v[94:97], v[130:133], v[188:191], v[94:97]
	v_mfma_f32_16x16x32_bf16 v[90:93], v[138:141], v[188:191], v[90:93]
	v_mfma_f32_16x16x32_bf16 v[126:129], v[130:133], v[148:151], v[126:129]
	v_mfma_f32_16x16x32_bf16 v[122:125], v[138:141], v[148:151], v[122:125]
	v_mfma_f32_16x16x32_bf16 v[118:121], v[134:137], v[176:179], v[118:121]
	v_mfma_f32_16x16x32_bf16 v[114:117], v[142:145], v[176:179], v[114:117]
	v_mfma_f32_16x16x32_bf16 v[110:113], v[134:137], v[184:187], v[110:113]
	v_mfma_f32_16x16x32_bf16 v[106:109], v[142:145], v[184:187], v[106:109]
	v_mfma_f32_16x16x32_bf16 v[94:97], v[134:137], v[192:195], v[94:97]
	v_mfma_f32_16x16x32_bf16 v[90:93], v[142:145], v[192:195], v[90:93]
	v_mfma_f32_16x16x32_bf16 v[126:129], v[134:137], v[168:171], v[126:129]
	v_mfma_f32_16x16x32_bf16 v[122:125], v[142:145], v[168:171], v[122:125]
	s_setprio 0
	s_barrier
; #define PG8_STAGE(bufoff, gbase, goff, voff) do { _Pragma("unroll") for (int _i = 0; _i < 2; ++_i) \
;     __builtin_amdgcn_global_load_lds((const unsigned*)((gbase) + (size_t)(goff) + (voff)[_i]), (LAS unsigned*)(lds + (bufoff) + ldsw + _i * 8192), 16, 0, 0); } while (0)
; #define PG8_LDA(dst, b, h) do { _Pragma("unroll") for (int m = 0; m < 4; ++m) _Pragma("unroll") for (int k = 0; k < 2; ++k) dst[m][k] = *(const LAS bf16x8*)(lds + PG8_SA(b, h) + aoff + m * 2048 + k * 1024); } while (0)
; #define PG8_LDB(dst, b, h) do { _Pragma("unroll") for (int n = 0; n < 2; ++n) _Pragma("unroll") for (int k = 0; k < 2; ++k) dst[n][k] = *(const LAS bf16x8*)(lds + PG8_SB(b, h) + boff + n * 2048 + k * 1024); } while (0)
; #define PG8_MMA(ai, bj, At, Bt) do { __builtin_amdgcn_s_setprio(1); _Pragma("unroll") for (int m = 0; m < 4; ++m) _Pragma("unroll") for (int n = 0; n < 2; ++n) _Pragma("unroll") for (int k = 0; k < 2; ++k) \
;     acc[ai][bj][m][n] = __builtin_amdgcn_mfma_f32_16x16x32_bf16(Bt[n][k], At[m][k], acc[ai][bj][m][n], 0, 0, 0); __builtin_amdgcn_s_setprio(0); } while (0)
; #define PG8_WAIT_V(n) asm volatile("s_waitcnt vmcnt(" #n ")" ::: "memory")
; #define PG8_WAIT_L(n) asm volatile("s_waitcnt lgkmcnt(" #n ")" ::: "memory")
; #define PG8_BAR __builtin_amdgcn_s_barrier()
; #define PG8_SCHED __builtin_amdgcn_sched_barrier(0)
; template <class Epi>
; DI void gemm_phase(LAS unsigned char* lds, const GemmD g, const Order& S, const Epi& E) {
;     ...
;       PG8_WAIT_L(8); PG8_BAR; PG8_WAIT_L(0); PG8_MMA(0, 0, At, B0); PG8_BAR; PG8_SCHED;
;       PG8_LDB(B1, 1, 1); PG8_STAGE(PG8_SB(1, 0), gB, b3, voffB);
;       PG8_BAR; PG8_WAIT_L(0); PG8_MMA(0, 1, At, B1); PG8_BAR;
;       PG8_LDA(At, 1, 1); PG8_STAGE(PG8_SA(1, 0), gA, a3, voffA);
;       PG8_BAR; PG8_WAIT_L(0); PG8_MMA(1, 0, At, B0); PG8_BAR; PG8_SCHED;
;       PG8_STAGE(PG8_SB(1, 1), gB, b3 + hstepB, voffB);
;       PG8_WAIT_V(6); PG8_BAR; PG8_MMA(1, 1, At, B1); PG8_BAR;
	s_add_i32 vcc_lo, 0, 0x1c000
	s_add_i32 s95, s95, s29
	v_add_u32_e32 v164, vcc_lo, v167
	v_lshl_add_u64 v[152:153], v[152:153], 0, s[58:59]
	s_mov_b32 m0, s95
	s_add_i32 s81, s95, 0x2000
	ds_read_b128 v[196:199], v164
	ds_read_b128 v[218:221], v164 offset:1024
	ds_read_b128 v[222:225], v164 offset:2048
	ds_read_b128 v[226:229], v164 offset:3072
	global_load_lds_dwordx4 v[152:153], off
	v_lshl_add_u64 v[152:153], v[158:159], 0, s[58:59]
	s_mov_b32 m0, s81
	s_nop 0
	global_load_lds_dwordx4 v[152:153], off
	s_barrier
	s_waitcnt lgkmcnt(0)
	s_setprio 1
	s_waitcnt lgkmcnt(0)
	v_mfma_f32_16x16x32_bf16 v[102:105], v[196:199], v[148:151], v[102:105]
	v_mfma_f32_16x16x32_bf16 v[98:101], v[222:225], v[148:151], v[98:101]
	v_mfma_f32_16x16x32_bf16 v[86:89], v[196:199], v[172:175], v[86:89]
	v_mfma_f32_16x16x32_bf16 v[82:85], v[222:225], v[172:175], v[82:85]
	v_mfma_f32_16x16x32_bf16 v[78:81], v[196:199], v[180:183], v[78:81]
	v_mfma_f32_16x16x32_bf16 v[74:77], v[222:225], v[180:183], v[74:77]
	v_mfma_f32_16x16x32_bf16 v[70:73], v[196:199], v[188:191], v[70:73]
	v_mfma_f32_16x16x32_bf16 v[66:69], v[222:225], v[188:191], v[66:69]
	v_mfma_f32_16x16x32_bf16 v[102:105], v[218:221], v[168:171], v[102:105]
	v_mfma_f32_16x16x32_bf16 v[98:101], v[226:229], v[168:171], v[98:101]
	v_mfma_f32_16x16x32_bf16 v[86:89], v[218:221], v[176:179], v[86:89]
	v_mfma_f32_16x16x32_bf16 v[82:85], v[226:229], v[176:179], v[82:85]
	v_mfma_f32_16x16x32_bf16 v[78:81], v[218:221], v[184:187], v[78:81]
	v_mfma_f32_16x16x32_bf16 v[74:77], v[226:229], v[184:187], v[74:77]
	v_mfma_f32_16x16x32_bf16 v[70:73], v[218:221], v[192:195], v[70:73]
	v_mfma_f32_16x16x32_bf16 v[66:69], v[226:229], v[192:195], v[66:69]
	s_setprio 0
	s_mov_b32 m0, s71
	v_lshl_add_u64 v[152:153], v[160:161], 0, s[58:59]
	s_barrier
	ds_read_b128 v[148:151], v216 offset:49152
	ds_read_b128 v[168:171], v216 offset:50176
	ds_read_b128 v[172:175], v216 offset:51200
	ds_read_b128 v[176:179], v216 offset:52224
	ds_read_b128 v[180:183], v216 offset:53248
	ds_read_b128 v[184:187], v216 offset:54272
	ds_read_b128 v[188:191], v216 offset:55296
	ds_read_b128 v[192:195], v216 offset:56320
	global_load_lds_dwordx4 v[152:153], off
	v_lshl_add_u64 v[152:153], v[162:163], 0, s[58:59]
	s_mov_b32 m0, s72
	s_nop 0
	global_load_lds_dwordx4 v[152:153], off
	s_barrier
	s_waitcnt lgkmcnt(0)
	s_setprio 1
	s_waitcnt lgkmcnt(0)
	v_mfma_f32_16x16x32_bf16 v[54:57], v[130:133], v[148:151], v[54:57]
	v_mfma_f32_16x16x32_bf16 v[50:53], v[138:141], v[148:151], v[50:53]
	v_mfma_f32_16x16x32_bf16 v[38:41], v[130:133], v[172:175], v[38:41]
	v_mfma_f32_16x16x32_bf16 v[34:37], v[138:141], v[172:175], v[34:37]
	v_mfma_f32_16x16x32_bf16 v[16:19], v[138:141], v[180:183], v[16:19]
	v_mfma_f32_16x16x32_bf16 v[62:65], v[130:133], v[188:191], v[62:65]
	v_mfma_f32_16x16x32_bf16 v[58:61], v[138:141], v[188:191], v[58:61]
	v_mfma_f32_16x16x32_bf16 v[54:57], v[134:137], v[168:171], v[54:57]
	v_mfma_f32_16x16x32_bf16 v[50:53], v[142:145], v[168:171], v[50:53]
	v_mfma_f32_16x16x32_bf16 v[38:41], v[134:137], v[176:179], v[38:41]
	v_mfma_f32_16x16x32_bf16 v[34:37], v[142:145], v[176:179], v[34:37]
	v_mfma_f32_16x16x32_bf16 v[24:27], v[130:133], v[180:183], v[24:27]
	v_mfma_f32_16x16x32_bf16 v[16:19], v[142:145], v[184:187], v[16:19]
	v_mfma_f32_16x16x32_bf16 v[62:65], v[134:137], v[192:195], v[62:65]
	v_mfma_f32_16x16x32_bf16 v[58:61], v[142:145], v[192:195], v[58:61]
	v_mfma_f32_16x16x32_bf16 v[24:27], v[134:137], v[184:187], v[24:27]
	s_setprio 0
	s_barrier
	s_add_i32 s8, s23, 0x40180
	s_add_u32 s8, s27, s8
	s_addc_u32 s9, s28, 0
	s_add_i32 vcc_lo, vcc_lo, s29
	v_lshl_add_u64 v[130:131], s[8:9], 0, v[32:33]
	s_mov_b32 m0, vcc_lo
	s_add_i32 s23, vcc_lo, 0x2000
	global_load_lds_dwordx4 v[130:131], off
	v_lshl_add_u64 v[130:131], s[8:9], 0, v[146:147]
	s_mov_b32 m0, s23
	s_nop 0
	global_load_lds_dwordx4 v[130:131], off
	s_waitcnt vmcnt(6)
	s_barrier
	s_setprio 1
	v_mfma_f32_16x16x32_bf16 v[28:31], v[196:199], v[148:151], v[28:31]
	v_mfma_f32_16x16x32_bf16 v[20:23], v[222:225], v[148:151], v[20:23]
	v_mfma_f32_16x16x32_bf16 v[12:15], v[196:199], v[172:175], v[12:15]
	v_mfma_f32_16x16x32_bf16 v[8:11], v[222:225], v[172:175], v[8:11]
	v_mfma_f32_16x16x32_bf16 v[4:7], v[196:199], v[180:183], v[4:7]
	v_mfma_f32_16x16x32_bf16 v[0:3], v[222:225], v[180:183], v[0:3]
	v_mfma_f32_16x16x32_bf16 v[46:49], v[196:199], v[188:191], v[46:49]
	v_mfma_f32_16x16x32_bf16 v[42:45], v[222:225], v[188:191], v[42:45]
	v_mfma_f32_16x16x32_bf16 v[28:31], v[218:221], v[168:171], v[28:31]
	v_mfma_f32_16x16x32_bf16 v[20:23], v[226:229], v[168:171], v[20:23]
	v_mfma_f32_16x16x32_bf16 v[12:15], v[218:221], v[176:179], v[12:15]
	v_mfma_f32_16x16x32_bf16 v[8:11], v[226:229], v[176:179], v[8:11]
	v_mfma_f32_16x16x32_bf16 v[4:7], v[218:221], v[184:187], v[4:7]
	v_mfma_f32_16x16x32_bf16 v[0:3], v[226:229], v[184:187], v[0:3]
	v_mfma_f32_16x16x32_bf16 v[46:49], v[218:221], v[192:195], v[46:49]
	v_mfma_f32_16x16x32_bf16 v[42:45], v[226:229], v[192:195], v[42:45]
	s_setprio 0
	s_barrier
	ds_read_b128 v[130:133], v200
	ds_read_b128 v[134:137], v200 offset:1024
	ds_read_b128 v[138:141], v200 offset:2048
	ds_read_b128 v[142:145], v200 offset:3072
	s_add_i32 s8, s22, 0x40180
	s_add_u32 s8, s14, s8
	s_addc_u32 s9, s15, 0
	s_mov_b32 m0, s90
	v_lshl_add_u64 v[152:153], s[8:9], 0, v[32:33]
	ds_read_b128 v[148:151], v216
	ds_read_b128 v[168:171], v216 offset:1024
	ds_read_b128 v[172:175], v216 offset:2048
	ds_read_b128 v[176:179], v216 offset:3072
	ds_read_b128 v[180:183], v216 offset:4096
	ds_read_b128 v[184:187], v216 offset:5120
	ds_read_b128 v[188:191], v216 offset:6144
	ds_read_b128 v[192:195], v216 offset:7168
	global_load_lds_dwordx4 v[152:153], off
	v_lshl_add_u64 v[152:153], s[8:9], 0, v[146:147]
	s_mov_b32 m0, s25
	s_nop 0
	global_load_lds_dwordx4 v[152:153], off
	s_waitcnt lgkmcnt(8)
	s_barrier
; #define PG8_STAGE(bufoff, gbase, goff, voff) do { _Pragma("unroll") for (int _i = 0; _i < 2; ++_i) \
;     __builtin_amdgcn_global_load_lds((const unsigned*)((gbase) + (size_t)(goff) + (voff)[_i]), (LAS unsigned*)(lds + (bufoff) + ldsw + _i * 8192), 16, 0, 0); } while (0)
; #define PG8_LDA(dst, b, h) do { _Pragma("unroll") for (int m = 0; m < 4; ++m) _Pragma("unroll") for (int k = 0; k < 2; ++k) dst[m][k] = *(const LAS bf16x8*)(lds + PG8_SA(b, h) + aoff + m * 2048 + k * 1024); } while (0)
; #define PG8_LDB(dst, b, h) do { _Pragma("unroll") for (int n = 0; n < 2; ++n) _Pragma("unroll") for (int k = 0; k < 2; ++k) dst[n][k] = *(const LAS bf16x8*)(lds + PG8_SB(b, h) + boff + n * 2048 + k * 1024); } while (0)
; #define PG8_MMA(ai, bj, At, Bt) do { __builtin_amdgcn_s_setprio(1); _Pragma("unroll") for (int m = 0; m < 4; ++m) _Pragma("unroll") for (int n = 0; n < 2; ++n) _Pragma("unroll") for (int k = 0; k < 2; ++k) \
;     acc[ai][bj][m][n] = __builtin_amdgcn_mfma_f32_16x16x32_bf16(Bt[n][k], At[m][k], acc[ai][bj][m][n], 0, 0, 0); __builtin_amdgcn_s_setprio(0); } while (0)
; #define PG8_WAIT_V(n) asm volatile("s_waitcnt vmcnt(" #n ")" ::: "memory")
; #define PG8_WAIT_L(n) asm volatile("s_waitcnt lgkmcnt(" #n ")" ::: "memory")
; #define PG8_BAR __builtin_amdgcn_s_barrier()
; #define PG8_SCHED __builtin_amdgcn_sched_barrier(0)
; template <class Epi>
; DI void gemm_phase(LAS unsigned char* lds, const GemmD g, const Order& S, const Epi& E) {
;     ...
;       PG8_LDB(B0, 0, 0); PG8_SCHED; PG8_LDA(At, 0, 0); PG8_STAGE(PG8_SA(1, 1), gA, a1 + hstepA, voffA);
;       PG8_WAIT_L(8); PG8_BAR; PG8_WAIT_L(0); PG8_MMA(0, 0, At, B0); PG8_BAR; PG8_SCHED;
;       PG8_LDB(B1, 0, 1); PG8_STAGE(PG8_SB(0, 0), gB, b2, voffB);
;       PG8_BAR; PG8_WAIT_L(0); PG8_MMA(0, 1, At, B1); PG8_BAR;
;       PG8_LDA(At, 0, 1); PG8_STAGE(PG8_SA(0, 0), gA, a2, voffA);
;       PG8_BAR; PG8_WAIT_L(0); PG8_MMA(1, 0, At, B0); PG8_BAR; PG8_SCHED;
;       PG8_STAGE(PG8_SB(0, 1), gB, b2 + hstepB, voffB);
;       PG8_WAIT_V(6); PG8_BAR; PG8_MMA(1, 1, At, B1); PG8_BAR;
;       PG8_LDB(B0, 1, 0); PG8_SCHED; PG8_LDA(At, 1, 0); PG8_STAGE(PG8_SA(0, 1), gA, a2 + hstepA, voffA);
;       PG8_WAIT_L(8); PG8_BAR; PG8_WAIT_L(0); PG8_MMA(0, 0, At, B0); PG8_BAR; PG8_SCHED;
	s_waitcnt lgkmcnt(0)
	s_setprio 1
	s_waitcnt lgkmcnt(0)
	v_mfma_f32_16x16x32_bf16 v[118:121], v[130:133], v[172:175], v[118:121]
	v_mfma_f32_16x16x32_bf16 v[114:117], v[138:141], v[172:175], v[114:117]
	v_mfma_f32_16x16x32_bf16 v[110:113], v[130:133], v[180:183], v[110:113]
	v_mfma_f32_16x16x32_bf16 v[106:109], v[138:141], v[180:183], v[106:109]
	v_mfma_f32_16x16x32_bf16 v[94:97], v[130:133], v[188:191], v[94:97]
	v_mfma_f32_16x16x32_bf16 v[90:93], v[138:141], v[188:191], v[90:93]
	v_mfma_f32_16x16x32_bf16 v[126:129], v[130:133], v[148:151], v[126:129]
	v_mfma_f32_16x16x32_bf16 v[122:125], v[138:141], v[148:151], v[122:125]
	v_mfma_f32_16x16x32_bf16 v[118:121], v[134:137], v[176:179], v[118:121]
	v_mfma_f32_16x16x32_bf16 v[114:117], v[142:145], v[176:179], v[114:117]
	v_mfma_f32_16x16x32_bf16 v[110:113], v[134:137], v[184:187], v[110:113]
	v_mfma_f32_16x16x32_bf16 v[106:109], v[142:145], v[184:187], v[106:109]
	v_mfma_f32_16x16x32_bf16 v[94:97], v[134:137], v[192:195], v[94:97]
	v_mfma_f32_16x16x32_bf16 v[90:93], v[142:145], v[192:195], v[90:93]
	v_mfma_f32_16x16x32_bf16 v[126:129], v[134:137], v[168:171], v[126:129]
	v_mfma_f32_16x16x32_bf16 v[122:125], v[142:145], v[168:171], v[122:125]
	s_setprio 0
	s_barrier
	s_add_u32 s8, s27, s6
	s_addc_u32 s9, s28, 0
	s_mov_b32 m0, s80
	v_lshl_add_u64 v[152:153], s[8:9], 0, v[32:33]
	ds_read_b128 v[196:199], v201
	ds_read_b128 v[218:221], v201 offset:1024
	ds_read_b128 v[222:225], v201 offset:2048
	ds_read_b128 v[226:229], v201 offset:3072
	global_load_lds_dwordx4 v[152:153], off
	v_lshl_add_u64 v[200:201], s[8:9], 0, v[146:147]
	s_mov_b32 m0, s48
	s_nop 0
	global_load_lds_dwordx4 v[200:201], off
	s_barrier
	s_waitcnt lgkmcnt(0)
	s_setprio 1
	s_waitcnt lgkmcnt(0)
	v_mfma_f32_16x16x32_bf16 v[102:105], v[196:199], v[148:151], v[102:105]
	v_mfma_f32_16x16x32_bf16 v[98:101], v[222:225], v[148:151], v[98:101]
	v_mfma_f32_16x16x32_bf16 v[86:89], v[196:199], v[172:175], v[86:89]
	v_mfma_f32_16x16x32_bf16 v[82:85], v[222:225], v[172:175], v[82:85]
	v_mfma_f32_16x16x32_bf16 v[78:81], v[196:199], v[180:183], v[78:81]
	v_mfma_f32_16x16x32_bf16 v[74:77], v[222:225], v[180:183], v[74:77]
	v_mfma_f32_16x16x32_bf16 v[66:69], v[222:225], v[188:191], v[66:69]
	v_mfma_f32_16x16x32_bf16 v[102:105], v[218:221], v[168:171], v[102:105]
	v_mfma_f32_16x16x32_bf16 v[98:101], v[226:229], v[168:171], v[98:101]
	v_mfma_f32_16x16x32_bf16 v[148:151], v[218:221], v[176:179], v[86:89]
	v_mfma_f32_16x16x32_bf16 v[168:171], v[226:229], v[176:179], v[82:85]
	v_mfma_f32_16x16x32_bf16 v[172:175], v[218:221], v[184:187], v[78:81]
	v_mfma_f32_16x16x32_bf16 v[176:179], v[226:229], v[184:187], v[74:77]
	v_mfma_f32_16x16x32_bf16 v[70:73], v[196:199], v[188:191], v[70:73]
	v_mfma_f32_16x16x32_bf16 v[184:187], v[226:229], v[192:195], v[66:69]
	v_mfma_f32_16x16x32_bf16 v[180:183], v[218:221], v[192:195], v[70:73]
	s_setprio 0
	s_add_u32 s8, s14, s7
	s_addc_u32 s9, s15, 0
	s_mov_b32 m0, s30
	v_lshl_add_u64 v[208:209], s[8:9], 0, v[32:33]
	s_barrier
	ds_read_b128 v[66:69], v216 offset:16384
	ds_read_b128 v[70:73], v216 offset:17408
	ds_read_b128 v[74:77], v216 offset:18432
	ds_read_b128 v[78:81], v216 offset:19456
	ds_read_b128 v[82:85], v216 offset:20480
	ds_read_b128 v[86:89], v216 offset:21504
	ds_read_b128 v[188:191], v216 offset:22528
	ds_read_b128 v[192:195], v216 offset:23552
	global_load_lds_dwordx4 v[208:209], off
	v_lshl_add_u64 v[204:205], s[8:9], 0, v[146:147]
	s_mov_b32 m0, s31
	s_nop 0
	global_load_lds_dwordx4 v[204:205], off
	s_barrier
	s_waitcnt lgkmcnt(0)
	s_setprio 1
	s_waitcnt lgkmcnt(0)
	v_mfma_f32_16x16x32_bf16 v[54:57], v[130:133], v[66:69], v[54:57]
	v_mfma_f32_16x16x32_bf16 v[50:53], v[138:141], v[66:69], v[50:53]
	v_mfma_f32_16x16x32_bf16 v[38:41], v[130:133], v[74:77], v[38:41]
	v_mfma_f32_16x16x32_bf16 v[34:37], v[138:141], v[74:77], v[34:37]
	v_mfma_f32_16x16x32_bf16 v[16:19], v[138:141], v[82:85], v[16:19]
	v_mfma_f32_16x16x32_bf16 v[62:65], v[130:133], v[188:191], v[62:65]
	v_mfma_f32_16x16x32_bf16 v[58:61], v[138:141], v[188:191], v[58:61]
	v_mfma_f32_16x16x32_bf16 v[54:57], v[134:137], v[70:73], v[54:57]
	v_mfma_f32_16x16x32_bf16 v[50:53], v[142:145], v[70:73], v[50:53]
	v_mfma_f32_16x16x32_bf16 v[38:41], v[134:137], v[78:81], v[38:41]
	v_mfma_f32_16x16x32_bf16 v[34:37], v[142:145], v[78:81], v[34:37]
	v_mfma_f32_16x16x32_bf16 v[24:27], v[130:133], v[82:85], v[24:27]
	v_mfma_f32_16x16x32_bf16 v[16:19], v[142:145], v[86:89], v[16:19]
	v_mfma_f32_16x16x32_bf16 v[130:133], v[134:137], v[192:195], v[62:65]
	v_mfma_f32_16x16x32_bf16 v[138:141], v[142:145], v[192:195], v[58:61]
	v_mfma_f32_16x16x32_bf16 v[24:27], v[134:137], v[86:89], v[24:27]
	s_setprio 0
	s_barrier
	s_add_i32 s8, s6, 0x40000
	s_add_u32 s8, s27, s8
	s_addc_u32 s9, s28, 0
	s_mov_b32 m0, s92
	v_lshl_add_u64 v[58:59], s[8:9], 0, v[32:33]
	global_load_lds_dwordx4 v[58:59], off
	v_lshl_add_u64 v[58:59], s[8:9], 0, v[146:147]
	s_mov_b32 m0, s79
	s_nop 0
	global_load_lds_dwordx4 v[58:59], off
	s_waitcnt vmcnt(6)
	s_barrier
	s_setprio 1
	v_mfma_f32_16x16x32_bf16 v[0:3], v[222:225], v[82:85], v[0:3]
	v_mfma_f32_16x16x32_bf16 v[28:31], v[196:199], v[66:69], v[28:31]
	v_mfma_f32_16x16x32_bf16 v[246:249], v[226:229], v[86:89], v[0:3]
	v_mfma_f32_16x16x32_bf16 v[0:3], v[196:199], v[188:191], v[46:49]
	v_mfma_f32_16x16x32_bf16 v[142:145], v[218:221], v[70:73], v[28:31]
	v_mfma_f32_16x16x32_bf16 v[20:23], v[222:225], v[66:69], v[20:23]
	v_mfma_f32_16x16x32_bf16 v[12:15], v[196:199], v[74:77], v[12:15]
	v_mfma_f32_16x16x32_bf16 v[8:11], v[222:225], v[74:77], v[8:11]
	v_mfma_f32_16x16x32_bf16 v[4:7], v[196:199], v[82:85], v[4:7]
	v_mfma_f32_16x16x32_bf16 v[196:199], v[218:221], v[192:195], v[0:3]
	v_mfma_f32_16x16x32_bf16 v[0:3], v[222:225], v[188:191], v[42:45]
	v_mfma_f32_16x16x32_bf16 v[230:233], v[226:229], v[70:73], v[20:23]
	v_mfma_f32_16x16x32_bf16 v[234:237], v[218:221], v[78:81], v[12:15]
	v_mfma_f32_16x16x32_bf16 v[238:241], v[226:229], v[78:81], v[8:11]
	v_mfma_f32_16x16x32_bf16 v[242:245], v[218:221], v[86:89], v[4:7]
	v_mfma_f32_16x16x32_bf16 v[188:191], v[226:229], v[192:195], v[0:3]
	s_setprio 0
	s_barrier
; #define PG8_STAGE(bufoff, gbase, goff, voff) do { _Pragma("unroll") for (int _i = 0; _i < 2; ++_i) \
;     __builtin_amdgcn_global_load_lds((const unsigned*)((gbase) + (size_t)(goff) + (voff)[_i]), (LAS unsigned*)(lds + (bufoff) + ldsw + _i * 8192), 16, 0, 0); } while (0)
; #define PG8_LDA(dst, b, h) do { _Pragma("unroll") for (int m = 0; m < 4; ++m) _Pragma("unroll") for (int k = 0; k < 2; ++k) dst[m][k] = *(const LAS bf16x8*)(lds + PG8_SA(b, h) + aoff + m * 2048 + k * 1024); } while (0)
; #define PG8_LDB(dst, b, h) do { _Pragma("unroll") for (int n = 0; n < 2; ++n) _Pragma("unroll") for (int k = 0; k < 2; ++k) dst[n][k] = *(const LAS bf16x8*)(lds + PG8_SB(b, h) + boff + n * 2048 + k * 1024); } while (0)
; #define PG8_MMA(ai, bj, At, Bt) do { __builtin_amdgcn_s_setprio(1); _Pragma("unroll") for (int m = 0; m < 4; ++m) _Pragma("unroll") for (int n = 0; n < 2; ++n) _Pragma("unroll") for (int k = 0; k < 2; ++k) \
;     acc[ai][bj][m][n] = __builtin_amdgcn_mfma_f32_16x16x32_bf16(Bt[n][k], At[m][k], acc[ai][bj][m][n], 0, 0, 0); __builtin_amdgcn_s_setprio(0); } while (0)
; #define PG8_WAIT_V(n) asm volatile("s_waitcnt vmcnt(" #n ")" ::: "memory")
; #define PG8_WAIT_L(n) asm volatile("s_waitcnt lgkmcnt(" #n ")" ::: "memory")
; #define PG8_BAR __builtin_amdgcn_s_barrier()
; #define PG8_SCHED __builtin_amdgcn_sched_barrier(0)
; template <class Epi>
; DI void gemm_phase(LAS unsigned char* lds, const GemmD g, const Order& S, const Epi& E) {
;     ...
;       PG8_LDA(At, 0, 1); PG8_STAGE(PG8_SA(0, 0), gA, a2, voffA);
;       PG8_BAR; PG8_WAIT_L(0); PG8_MMA(1, 0, At, B0); PG8_BAR; PG8_SCHED;
;       PG8_STAGE(PG8_SB(0, 1), gB, b2 + hstepB, voffB);
;       PG8_WAIT_V(6); PG8_BAR; PG8_MMA(1, 1, At, B1); PG8_BAR;
;       PG8_LDB(B0, 1, 0); PG8_SCHED; PG8_LDA(At, 1, 0); PG8_STAGE(PG8_SA(0, 1), gA, a2 + hstepA, voffA);
;       PG8_WAIT_L(8); PG8_BAR; PG8_WAIT_L(0); PG8_MMA(0, 0, At, B0); PG8_BAR; PG8_SCHED;
;       PG8_LDB(B1, 1, 1); PG8_STAGE(PG8_SB(1, 0), gB, b3, voffB);
;       PG8_BAR; PG8_WAIT_L(0); PG8_MMA(0, 1, At, B1); PG8_BAR;
;       PG8_LDA(At, 1, 1); PG8_STAGE(PG8_SA(1, 0), gA, a3, voffA);
	ds_read_b128 v[134:137], v217
	ds_read_b128 v[192:195], v217 offset:1024
	ds_read_b128 v[218:221], v217 offset:2048
	ds_read_b128 v[222:225], v217 offset:3072
	s_add_i32 s7, s7, 0x40000
	s_add_u32 s8, s14, s7
	s_addc_u32 s9, s15, 0
	s_mov_b32 m0, s65
	v_lshl_add_u64 v[42:43], s[8:9], 0, v[32:33]
	ds_read_b128 v[0:3], v216 offset:32768
	ds_read_b128 v[4:7], v216 offset:33792
	ds_read_b128 v[8:11], v216 offset:34816
	ds_read_b128 v[12:15], v216 offset:35840
	ds_read_b128 v[20:23], v216 offset:36864
	ds_read_b128 v[28:31], v216 offset:37888
	ds_read_b128 v[226:229], v216 offset:38912
	ds_read_b128 v[250:253], v216 offset:39936
	global_load_lds_dwordx4 v[42:43], off
	v_lshl_add_u64 v[42:43], s[8:9], 0, v[146:147]
	s_mov_b32 m0, s66
	s_nop 0
	global_load_lds_dwordx4 v[42:43], off
	s_waitcnt lgkmcnt(8)
	s_barrier
	s_waitcnt lgkmcnt(0)
	s_setprio 1
	s_waitcnt lgkmcnt(0)
	v_mfma_f32_16x16x32_bf16 v[58:61], v[134:137], v[8:11], v[118:121]
	v_mfma_f32_16x16x32_bf16 v[86:89], v[192:195], v[12:15], v[58:61]
	v_mfma_f32_16x16x32_bf16 v[58:61], v[218:221], v[8:11], v[114:117]
	v_mfma_f32_16x16x32_bf16 v[82:85], v[222:225], v[12:15], v[58:61]
	v_mfma_f32_16x16x32_bf16 v[58:61], v[134:137], v[20:23], v[110:113]
	v_mfma_f32_16x16x32_bf16 v[78:81], v[192:195], v[28:31], v[58:61]
	v_mfma_f32_16x16x32_bf16 v[58:61], v[218:221], v[20:23], v[106:109]
	v_mfma_f32_16x16x32_bf16 v[42:45], v[134:137], v[0:3], v[126:129]
	v_mfma_f32_16x16x32_bf16 v[74:77], v[222:225], v[28:31], v[58:61]
	v_mfma_f32_16x16x32_bf16 v[58:61], v[134:137], v[226:229], v[94:97]
	v_mfma_f32_16x16x32_bf16 v[46:49], v[192:195], v[4:7], v[42:45]
	v_mfma_f32_16x16x32_bf16 v[42:45], v[218:221], v[0:3], v[122:125]
	v_mfma_f32_16x16x32_bf16 v[70:73], v[192:195], v[250:253], v[58:61]
	v_mfma_f32_16x16x32_bf16 v[58:61], v[218:221], v[226:229], v[90:93]
	v_mfma_f32_16x16x32_bf16 v[42:45], v[222:225], v[4:7], v[42:45]
	v_mfma_f32_16x16x32_bf16 v[66:69], v[222:225], v[250:253], v[58:61]
	s_setprio 0
	s_barrier
	s_mov_b32 m0, s95
	s_nop 2
	v_lshl_add_u64 v[58:59], v[152:153], 0, s[50:51]
	ds_read_b128 v[122:125], v164
	ds_read_b128 v[126:129], v164 offset:1024
	ds_read_b128 v[158:161], v164 offset:2048
	ds_read_b128 v[162:165], v164 offset:3072
	global_load_lds_dwordx4 v[58:59], off
	v_lshl_add_u64 v[58:59], v[200:201], 0, s[50:51]
	s_mov_b32 m0, s81
	s_nop 0
	global_load_lds_dwordx4 v[58:59], off
	s_barrier
	s_waitcnt lgkmcnt(0)
	s_setprio 1
	s_waitcnt lgkmcnt(0)
	v_mfma_f32_16x16x32_bf16 v[58:61], v[122:125], v[0:3], v[102:105]
	v_mfma_f32_16x16x32_bf16 v[0:3], v[158:161], v[0:3], v[98:101]
	v_mfma_f32_16x16x32_bf16 v[62:65], v[126:129], v[4:7], v[58:61]
	v_mfma_f32_16x16x32_bf16 v[58:61], v[162:165], v[4:7], v[0:3]
	v_mfma_f32_16x16x32_bf16 v[0:3], v[122:125], v[8:11], v[148:151]
	v_mfma_f32_16x16x32_bf16 v[102:105], v[126:129], v[12:15], v[0:3]
	v_mfma_f32_16x16x32_bf16 v[0:3], v[158:161], v[8:11], v[168:171]
	v_mfma_f32_16x16x32_bf16 v[98:101], v[162:165], v[12:15], v[0:3]
	v_mfma_f32_16x16x32_bf16 v[0:3], v[122:125], v[20:23], v[172:175]
	v_mfma_f32_16x16x32_bf16 v[118:121], v[126:129], v[28:31], v[0:3]
	v_mfma_f32_16x16x32_bf16 v[0:3], v[158:161], v[20:23], v[176:179]
	v_mfma_f32_16x16x32_bf16 v[114:117], v[162:165], v[28:31], v[0:3]
	v_mfma_f32_16x16x32_bf16 v[0:3], v[122:125], v[226:229], v[180:183]
	v_mfma_f32_16x16x32_bf16 v[110:113], v[126:129], v[250:253], v[0:3]
	v_mfma_f32_16x16x32_bf16 v[0:3], v[158:161], v[226:229], v[184:187]
	v_mfma_f32_16x16x32_bf16 v[106:109], v[162:165], v[250:253], v[0:3]
	s_setprio 0
	s_mov_b32 m0, s71
	s_nop 4
	v_lshl_add_u64 v[0:1], v[208:209], 0, s[50:51]
	s_barrier
	ds_read_b128 v[90:93], v216 offset:49152
	ds_read_b128 v[148:151], v216 offset:50176
	ds_read_b128 v[168:171], v216 offset:51200
	ds_read_b128 v[172:175], v216 offset:52224
	ds_read_b128 v[176:179], v216 offset:53248
	ds_read_b128 v[180:183], v216 offset:54272
	ds_read_b128 v[184:187], v216 offset:55296
	ds_read_b128 v[226:229], v216 offset:56320
	global_load_lds_dwordx4 v[0:1], off
	v_lshl_add_u64 v[0:1], v[204:205], 0, s[50:51]
	s_mov_b32 m0, s72
	s_nop 0
	global_load_lds_dwordx4 v[0:1], off
	s_barrier
; #define PG8_STAGE(bufoff, gbase, goff, voff) do { _Pragma("unroll") for (int _i = 0; _i < 2; ++_i) \
;     __builtin_amdgcn_global_load_lds((const unsigned*)((gbase) + (size_t)(goff) + (voff)[_i]), (LAS unsigned*)(lds + (bufoff) + ldsw + _i * 8192), 16, 0, 0); } while (0)
; #define PG8_LDA(dst, b, h) do { _Pragma("unroll") for (int m = 0; m < 4; ++m) _Pragma("unroll") for (int k = 0; k < 2; ++k) dst[m][k] = *(const LAS bf16x8*)(lds + PG8_SA(b, h) + aoff + m * 2048 + k * 1024); } while (0)
; #define PG8_MMA(ai, bj, At, Bt) do { __builtin_amdgcn_s_setprio(1); _Pragma("unroll") for (int m = 0; m < 4; ++m) _Pragma("unroll") for (int n = 0; n < 2; ++n) _Pragma("unroll") for (int k = 0; k < 2; ++k) \
;     acc[ai][bj][m][n] = __builtin_amdgcn_mfma_f32_16x16x32_bf16(Bt[n][k], At[m][k], acc[ai][bj][m][n], 0, 0, 0); __builtin_amdgcn_s_setprio(0); } while (0)
; #define PG8_WAIT_V(n) asm volatile("s_waitcnt vmcnt(" #n ")" ::: "memory")
; #define PG8_WAIT_L(n) asm volatile("s_waitcnt lgkmcnt(" #n ")" ::: "memory")
; #define PG8_BAR __builtin_amdgcn_s_barrier()
; template <class Epi>
; DI void gemm_phase(LAS unsigned char* lds, const GemmD g, const Order& S, const Epi& E) {
;     ...
;       PG8_BAR; PG8_WAIT_L(0); PG8_MMA(0, 1, At, B1); PG8_BAR;
;       PG8_LDA(At, 1, 1); PG8_STAGE(PG8_SA(1, 0), gA, a3, voffA);
;       PG8_BAR; PG8_WAIT_L(0); PG8_MMA(1, 0, At, B0); PG8_BAR; PG8_SCHED;
;       PG8_STAGE(PG8_SB(1, 1), gB, b3 + hstepB, voffB);
;       PG8_WAIT_V(6); PG8_BAR; PG8_MMA(1, 1, At, B1); PG8_BAR;
;   DI bool operator()(f32x4 (&acc)[2][2][4][2], const Unit& u, int, int, int, int) const {
;     ...
;       for (int ai = 0; ai < 2; ++ai)
; #pragma unroll
;         for (int m = 0; m < 4; ++m) {
;           const int r = row0 + ai * HALF + m * 16;
;           const f32x4 q0 = *(const f32x4*)(ss + ((size_t)r * 4 + u.kg) * 4);
;           const float s0 = (q0[0] + q0[1] + q0[2] + q0[3]) * (1.f / 256.f) + 1e-6f;
;           float f;
;           if (u.kg < 3) { const f32x4 q1 = *(const f32x4*)(ss + ((size_t)r * 4 + u.kg + 1) * 4);
;             const float s1 = (q1[0] + q1[1] + q1[2] + q1[3]) * (1.f / 256.f) + 1e-6f; f = __builtin_amdgcn_sqrtf(s1) * __builtin_amdgcn_rsqf(s0); }
;           else f = __builtin_amdgcn_rsqf(s0);
; #pragma unroll
;           for (int bj = 0; bj < 2; ++bj)
; #pragma unroll
;             for (int n = 0; n < 2; ++n) acc[ai][bj][m][n] *= f;
;         }
	s_waitcnt lgkmcnt(0)
	s_setprio 1
	s_waitcnt lgkmcnt(0)
	v_mfma_f32_16x16x32_bf16 v[0:3], v[134:137], v[90:93], v[54:57]
	v_mfma_f32_16x16x32_bf16 v[28:31], v[192:195], v[148:151], v[0:3]
	v_mfma_f32_16x16x32_bf16 v[0:3], v[218:221], v[90:93], v[50:53]
	v_mfma_f32_16x16x32_bf16 v[20:23], v[222:225], v[148:151], v[0:3]
	v_mfma_f32_16x16x32_bf16 v[0:3], v[134:137], v[168:171], v[38:41]
	v_mfma_f32_16x16x32_bf16 v[12:15], v[192:195], v[172:175], v[0:3]
	v_mfma_f32_16x16x32_bf16 v[0:3], v[218:221], v[168:171], v[34:37]
	v_mfma_f32_16x16x32_bf16 v[8:11], v[222:225], v[172:175], v[0:3]
	v_mfma_f32_16x16x32_bf16 v[0:3], v[134:137], v[176:179], v[24:27]
	v_mfma_f32_16x16x32_bf16 v[4:7], v[192:195], v[180:183], v[0:3]
	v_mfma_f32_16x16x32_bf16 v[0:3], v[218:221], v[176:179], v[16:19]
	v_mfma_f32_16x16x32_bf16 v[16:19], v[134:137], v[184:187], v[130:133]
	v_mfma_f32_16x16x32_bf16 v[134:137], v[192:195], v[226:229], v[16:19]
	v_mfma_f32_16x16x32_bf16 v[16:19], v[218:221], v[184:187], v[138:141]
	v_mfma_f32_16x16x32_bf16 v[0:3], v[222:225], v[180:183], v[0:3]
	v_mfma_f32_16x16x32_bf16 v[130:133], v[222:225], v[226:229], v[16:19]
	s_setprio 0
	s_barrier
	s_add_i32 s6, s6, 0x40080
	s_add_u32 s6, s27, s6
	s_addc_u32 s7, s28, 0
	s_mov_b32 m0, vcc_lo
	v_lshl_add_u64 v[16:17], s[6:7], 0, v[32:33]
	global_load_lds_dwordx4 v[16:17], off
	v_lshl_add_u64 v[16:17], s[6:7], 0, v[146:147]
	s_mov_b32 m0, s23
	s_nop 0
	global_load_lds_dwordx4 v[16:17], off
	s_waitcnt vmcnt(6)
	s_barrier
	s_setprio 1
	v_mfma_f32_16x16x32_bf16 v[16:19], v[122:125], v[90:93], v[142:145]
	v_mfma_f32_16x16x32_bf16 v[94:97], v[126:129], v[148:151], v[16:19]
	v_mfma_f32_16x16x32_bf16 v[16:19], v[158:161], v[90:93], v[230:233]
	v_mfma_f32_16x16x32_bf16 v[90:93], v[162:165], v[148:151], v[16:19]
	v_mfma_f32_16x16x32_bf16 v[16:19], v[122:125], v[168:171], v[234:237]
	v_mfma_f32_16x16x32_bf16 v[54:57], v[126:129], v[172:175], v[16:19]
	v_mfma_f32_16x16x32_bf16 v[16:19], v[158:161], v[168:171], v[238:241]
	v_mfma_f32_16x16x32_bf16 v[50:53], v[162:165], v[172:175], v[16:19]
	v_mfma_f32_16x16x32_bf16 v[16:19], v[122:125], v[176:179], v[242:245]
	v_mfma_f32_16x16x32_bf16 v[38:41], v[126:129], v[180:183], v[16:19]
	v_mfma_f32_16x16x32_bf16 v[16:19], v[158:161], v[176:179], v[246:249]
	v_mfma_f32_16x16x32_bf16 v[34:37], v[162:165], v[180:183], v[16:19]
	v_mfma_f32_16x16x32_bf16 v[16:19], v[122:125], v[184:187], v[196:199]
	v_mfma_f32_16x16x32_bf16 v[142:145], v[126:129], v[226:229], v[16:19]
	v_mfma_f32_16x16x32_bf16 v[16:19], v[158:161], v[184:187], v[188:191]
	v_mfma_f32_16x16x32_bf16 v[138:141], v[162:165], v[226:229], v[16:19]
	s_setprio 0
	v_mov_b32_e32 v196, v202
	s_barrier
	s_lshl_b32 s48, s24, 4
	s_nop 2
	v_ashrrev_i32_e32 v16, 2, v196
	v_and_b32_e32 v16, 0xffffffc0, v16
	v_lshl_add_u32 v16, s38, 8, v16
	v_and_or_b32 v186, v196, 15, v16
	v_ashrrev_i32_e32 v187, 31, v186
	v_lshlrev_b64 v[16:17], 6, v[186:187]
	v_lshl_add_u64 v[16:17], s[16:17], 0, v[16:17]
	v_lshl_add_u64 v[16:17], v[16:17], 0, s[48:49]
	s_cmp_eq_u32 s24, 3
	s_cselect_b64 s[22:23], -1, 0
	s_cmp_lg_u32 s24, 3
	s_cselect_b64 s[6:7], -1, 0
	v_or_b32_e32 v194, 16, v186
	v_ashrrev_i32_e32 v195, 31, v194
	v_or_b32_e32 v192, 32, v186
	v_ashrrev_i32_e32 v193, 31, v192
	v_or_b32_e32 v190, 48, v186
	v_ashrrev_i32_e32 v191, 31, v190
	v_add_u32_e32 v188, 0x80, v186
	v_ashrrev_i32_e32 v189, 31, v188
	v_add_u32_e32 v184, 0x90, v186
	v_ashrrev_i32_e32 v185, 31, v184
	v_add_u32_e32 v182, 0xa0, v186
	v_ashrrev_i32_e32 v183, 31, v182
	v_add_u32_e32 v148, 0xb0, v186
	v_ashrrev_i32_e32 v149, 31, v148
	s_lshl_b32 s8, s38, 8
	v_subrev_u32_e32 v16, s8, v186
	s_lshl_b32 s8, s98, 12
	s_lshl_b32 s9, s24, 2
	s_add_i32 s8, s8, s9
	s_add_i32 s8, s8, 0x20080
	v_lshl_add_u32 v16, v16, 4, s8
	ds_read_b32 v150, v16
	ds_read_b32 v122, v16 offset:256
	ds_read_b32 v124, v16 offset:512
	ds_read_b32 v126, v16 offset:768
	ds_read_b32 v128, v16 offset:2048
	ds_read_b32 v168, v16 offset:2304
	ds_read_b32 v170, v16 offset:2560
	ds_read_b32 v152, v16 offset:2816
	s_waitcnt lgkmcnt(0)

; __global__ void __launch_bounds__(512, 2) k_mega(P p) {
	.amdhsa_kernel _Z6k_mega1P
		.amdhsa_group_segment_fixed_size 8448
		.amdhsa_private_segment_fixed_size 0
		.amdhsa_kernarg_size 792
		.amdhsa_user_sgpr_count 2
		.amdhsa_user_sgpr_dispatch_ptr 0
		.amdhsa_user_sgpr_queue_ptr 0
		.amdhsa_user_sgpr_kernarg_segment_ptr 1
		.amdhsa_user_sgpr_dispatch_id 0
		.amdhsa_user_sgpr_kernarg_preload_length 0
		.amdhsa_user_sgpr_kernarg_preload_offset 0
		.amdhsa_user_sgpr_private_segment_size 0
		.amdhsa_uses_dynamic_stack 0
		.amdhsa_enable_private_segment 0
		.amdhsa_system_sgpr_workgroup_id_x 1
		.amdhsa_system_sgpr_workgroup_id_y 0
		.amdhsa_system_sgpr_workgroup_id_z 0
		.amdhsa_system_sgpr_workgroup_info 0
		.amdhsa_system_vgpr_workitem_id 2
		.amdhsa_next_free_vgpr 256
		.amdhsa_next_free_sgpr 99
		.amdhsa_accum_offset 256
		.amdhsa_reserve_vcc 1
		.amdhsa_float_round_mode_32 0
		.amdhsa_float_round_mode_16_64 0
		.amdhsa_float_denorm_mode_32 3
		.amdhsa_float_denorm_mode_16_64 3
		.amdhsa_dx10_clamp 1
		.amdhsa_ieee_mode 1
		.amdhsa_fp16_overflow 0
		.amdhsa_tg_split 0
		.amdhsa_exception_fp_ieee_invalid_op 0
		.amdhsa_exception_fp_denorm_src 0
		.amdhsa_exception_fp_ieee_div_zero 0
		.amdhsa_exception_fp_ieee_overflow 0
		.amdhsa_exception_fp_ieee_underflow 0
		.amdhsa_exception_fp_ieee_inexact 0
		.amdhsa_exception_int_div_zero 0
	.end_amdhsa_kernel

; __global__ void __launch_bounds__(512, 2) k_mega(P p) {
amdhsa.kernels:
  - .agpr_count:     0
    .args:
      - .offset:         0
        .size:           536
        .value_kind:     by_value
      - .offset:         536
        .size:           4
        .value_kind:     hidden_block_count_x
      - .offset:         540
        .size:           4
        .value_kind:     hidden_block_count_y
      - .offset:         544
        .size:           4
        .value_kind:     hidden_block_count_z
      - .offset:         548
        .size:           2
        .value_kind:     hidden_group_size_x
      - .offset:         550
        .size:           2
        .value_kind:     hidden_group_size_y
      - .offset:         552
        .size:           2
        .value_kind:     hidden_group_size_z
      - .offset:         554
        .size:           2
        .value_kind:     hidden_remainder_x
      - .offset:         556
        .size:           2
        .value_kind:     hidden_remainder_y
      - .offset:         558
        .size:           2
        .value_kind:     hidden_remainder_z
      - .offset:         576
        .size:           8
        .value_kind:     hidden_global_offset_x
      - .offset:         584
        .size:           8
        .value_kind:     hidden_global_offset_y
      - .offset:         592
        .size:           8
        .value_kind:     hidden_global_offset_z
      - .offset:         600
        .size:           2
        .value_kind:     hidden_grid_dims
      - .offset:         624
        .size:           8
        .value_kind:     hidden_multigrid_sync_arg
      - .offset:         656
        .size:           4
        .value_kind:     hidden_dynamic_lds_size
    .group_segment_fixed_size: 8448
    .kernarg_segment_align: 8
    .kernarg_segment_size: 792
    .language:       OpenCL C
    .language_version:
      - 2
      - 0
    .max_flat_workgroup_size: 512
    .name:           _Z6k_mega1P
    .private_segment_fixed_size: 0
    .sgpr_count:     105
    .sgpr_spill_count: 44
    .symbol:         _Z6k_mega1P.kd
    .uniform_work_group_size: 1
    .uses_dynamic_stack: false
    .vgpr_count:     256
    .vgpr_spill_count: 0
    .wavefront_size: 64
